# grid barrier: XCD leader issues L2 write-back first and the L1 invalidate right behind it (non-leaders invalidate before their first poll)
# baseline (speedup 1.0000x reference)
.LBB0_60:
	s_or_b64 exec, exec, s[8:9]
	v_cvt_f32_u32_e32 v4, v2
	s_waitcnt vmcnt(0)
	v_readfirstlane_b32 s3, v3
	v_sub_u32_e32 v3, 0, v2
	v_rcp_iflag_f32_e32 v4, v4
	v_add_u32_e32 v5, s3, v1
	v_mul_f32_e32 v4, 0x4f7ffffe, v4
	v_cvt_u32_f32_e32 v4, v4
	v_mul_lo_u32 v1, v3, v4
	v_mul_hi_u32 v1, v4, v1
	v_add_u32_e32 v1, v4, v1
	v_mul_hi_u32 v1, v5, v1
	v_mul_lo_u32 v3, v1, v2
	v_sub_u32_e32 v3, v5, v3
	v_add_u32_e32 v4, 1, v1
	v_cmp_ge_u32_e32 vcc, v3, v2
	s_nop 1
	v_cndmask_b32_e32 v1, v1, v4, vcc
	v_sub_u32_e32 v4, v3, v2
	v_cndmask_b32_e32 v3, v3, v4, vcc
	v_add_u32_e32 v4, 1, v1
	v_cmp_ge_u32_e32 vcc, v3, v2
	v_add_u32_e32 v3, 1, v5
	s_nop 0
	v_cndmask_b32_e32 v1, v1, v4, vcc
	v_mul_lo_u32 v4, v2, v1
	v_add_u32_e32 v2, v4, v2
	v_cmp_ne_u32_e32 vcc, v3, v2
	s_and_saveexec_b64 s[6:7], vcc
	s_xor_b64 s[6:7], exec, s[6:7]
	s_cbranch_execz .LBB0_74
	s_waitcnt lgkmcnt(0)
	buffer_inv sc1
	v_add_u32_e32 v1, 1, v1
	v_mul_lo_u32 v1, v1, v0
	s_add_u32 s12, s24, 0xed25400
	s_addc_u32 s13, s25, 0
	v_mov_b32_e32 v0, 0
	global_load_dword v0, v0, s[12:13] sc1
	s_waitcnt vmcnt(0)
	v_cmp_lt_u32_e32 vcc, v0, v1
	s_and_saveexec_b64 s[8:9], vcc
	s_cbranch_execz .LBB0_73
	s_add_u32 s10, s24, 0xed22200
	s_addc_u32 s11, s25, 0
	s_mov_b32 s3, 1
	s_mov_b64 s[14:15], 0
	v_mov_b32_e32 v0, 0
	s_branch .LBB0_64

.LBB0_74:
	s_andn2_saveexec_b64 s[6:7], s[6:7]
	s_cbranch_execz .LBB0_94
	s_mov_b64 s[6:7], exec
	buffer_wbl2 sc1
	buffer_inv sc1
	s_waitcnt lgkmcnt(0)
	s_waitcnt vmcnt(0)
	v_mbcnt_lo_u32_b32 v1, s6, 0
	v_mbcnt_hi_u32_b32 v1, s7, v1
	v_cmp_eq_u32_e32 vcc, 0, v1
	s_and_saveexec_b64 s[8:9], vcc
	s_cbranch_execz .LBB0_77
	s_bcnt1_i32_b64 s3, s[6:7]
	v_mov_b32_e32 v2, 0xed25000
	v_mov_b32_e32 v3, s3
	global_atomic_add v2, v2, v3, s[24:25] offset:1024 sc0

.LBB0_202:
	s_andn2_saveexec_b64 s[6:7], s[6:7]
	s_cbranch_execz .LBB0_222
	s_mov_b64 s[8:9], exec
	buffer_wbl2 sc1
	buffer_inv sc1
	s_waitcnt lgkmcnt(0)
	s_waitcnt vmcnt(0)
	v_mbcnt_lo_u32_b32 v1, s8, 0
	v_mbcnt_hi_u32_b32 v1, s9, v1
	v_cmp_eq_u32_e32 vcc, 0, v1
	s_and_saveexec_b64 s[10:11], vcc
	s_cbranch_execz .LBB0_205
	s_bcnt1_i32_b64 s3, s[8:9]
	v_mov_b32_e32 v2, 0xed25000
	v_mov_b32_e32 v3, s3
	global_atomic_add v2, v2, v3, s[24:25] offset:1024 sc0

.LBB0_954:
	s_or_b64 exec, exec, s[12:13]
	v_cvt_f32_u32_e32 v4, v2
	s_waitcnt vmcnt(0)
	v_readfirstlane_b32 s3, v3
	v_sub_u32_e32 v3, 0, v2
	v_rcp_iflag_f32_e32 v4, v4
	v_add_u32_e32 v5, s3, v1
	v_mul_f32_e32 v4, 0x4f7ffffe, v4
	v_cvt_u32_f32_e32 v4, v4
	v_mul_lo_u32 v1, v3, v4
	v_mul_hi_u32 v1, v4, v1
	v_add_u32_e32 v1, v4, v1
	v_mul_hi_u32 v1, v5, v1
	v_mul_lo_u32 v3, v1, v2
	v_sub_u32_e32 v3, v5, v3
	v_add_u32_e32 v4, 1, v1
	v_cmp_ge_u32_e32 vcc, v3, v2
	s_nop 1
	v_cndmask_b32_e32 v1, v1, v4, vcc
	v_sub_u32_e32 v4, v3, v2
	v_cndmask_b32_e32 v3, v3, v4, vcc
	v_add_u32_e32 v4, 1, v1
	v_cmp_ge_u32_e32 vcc, v3, v2
	v_add_u32_e32 v3, 1, v5
	s_nop 0
	v_cndmask_b32_e32 v1, v1, v4, vcc
	v_mul_lo_u32 v4, v2, v1
	v_add_u32_e32 v2, v4, v2
	v_cmp_ne_u32_e32 vcc, v3, v2
	s_and_saveexec_b64 s[10:11], vcc
	s_xor_b64 s[10:11], exec, s[10:11]
	s_cbranch_execz .LBB0_968
	s_waitcnt lgkmcnt(0)
	buffer_inv sc1
	v_add_u32_e32 v1, 1, v1
	v_mul_lo_u32 v1, v1, v0
	s_add_u32 s42, s24, 0xed25400
	s_addc_u32 s43, s25, 0
	v_mov_b32_e32 v0, 0
	global_load_dword v0, v0, s[42:43] sc1
	s_waitcnt vmcnt(0)
	v_cmp_lt_u32_e32 vcc, v0, v1
	s_and_saveexec_b64 s[12:13], vcc
	s_cbranch_execz .LBB0_967
	s_add_u32 s40, s24, 0xed22200
	s_addc_u32 s41, s25, 0
	s_mov_b32 s3, 1
	s_mov_b64 s[46:47], 0
	v_mov_b32_e32 v0, 0
	s_branch .LBB0_958

.LBB0_968:
	s_andn2_saveexec_b64 s[10:11], s[10:11]
	s_cbranch_execz .LBB0_988
	s_mov_b64 s[12:13], exec
	buffer_wbl2 sc1
	buffer_inv sc1
	s_waitcnt lgkmcnt(0)
	s_waitcnt vmcnt(0)
	v_mbcnt_lo_u32_b32 v1, s12, 0
	v_mbcnt_hi_u32_b32 v1, s13, v1
	v_cmp_eq_u32_e32 vcc, 0, v1
	s_and_saveexec_b64 s[16:17], vcc
	s_cbranch_execz .LBB0_971
	s_bcnt1_i32_b64 s3, s[12:13]
	v_mov_b32_e32 v2, 0xed25000
	v_mov_b32_e32 v3, s3
	global_atomic_add v2, v2, v3, s[24:25] offset:1024 sc0

.LBB0_1090:
	s_or_b64 exec, exec, s[16:17]
	v_cvt_f32_u32_e32 v4, v2
	s_waitcnt vmcnt(0)
	v_readfirstlane_b32 s3, v3
	v_sub_u32_e32 v3, 0, v2
	v_rcp_iflag_f32_e32 v4, v4
	v_add_u32_e32 v5, s3, v1
	v_mul_f32_e32 v4, 0x4f7ffffe, v4
	v_cvt_u32_f32_e32 v4, v4
	v_mul_lo_u32 v1, v3, v4
	v_mul_hi_u32 v1, v4, v1
	v_add_u32_e32 v1, v4, v1
	v_mul_hi_u32 v1, v5, v1
	v_mul_lo_u32 v3, v1, v2
	v_sub_u32_e32 v3, v5, v3
	v_add_u32_e32 v4, 1, v1
	v_cmp_ge_u32_e32 vcc, v3, v2
	s_nop 1
	v_cndmask_b32_e32 v1, v1, v4, vcc
	v_sub_u32_e32 v4, v3, v2
	v_cndmask_b32_e32 v3, v3, v4, vcc
	v_add_u32_e32 v4, 1, v1
	v_cmp_ge_u32_e32 vcc, v3, v2
	v_add_u32_e32 v3, 1, v5
	s_nop 0
	v_cndmask_b32_e32 v1, v1, v4, vcc
	v_mul_lo_u32 v4, v2, v1
	v_add_u32_e32 v2, v4, v2
	v_cmp_ne_u32_e32 vcc, v3, v2
	s_and_saveexec_b64 s[6:7], vcc
	s_xor_b64 s[6:7], exec, s[6:7]
	s_cbranch_execz .LBB0_1104
	s_waitcnt lgkmcnt(0)
	buffer_inv sc1
	v_add_u32_e32 v1, 1, v1
	v_mul_lo_u32 v1, v1, v0
	s_add_u32 s46, s24, 0xed25400
	s_addc_u32 s47, s25, 0
	v_mov_b32_e32 v0, 0
	global_load_dword v0, v0, s[46:47] sc1
	s_waitcnt vmcnt(0)
	v_cmp_lt_u32_e32 vcc, v0, v1
	s_and_saveexec_b64 s[40:41], vcc
	s_cbranch_execz .LBB0_1103
	s_add_u32 s42, s24, 0xed22200
	s_addc_u32 s43, s25, 0
	s_mov_b32 s3, 1
	s_mov_b64 s[48:49], 0
	v_mov_b32_e32 v0, 0
	s_branch .LBB0_1094

.LBB0_1104:
	s_andn2_saveexec_b64 s[6:7], s[6:7]
	s_cbranch_execz .LBB0_1124
	s_mov_b64 s[16:17], exec
	buffer_wbl2 sc1
	buffer_inv sc1
	s_waitcnt lgkmcnt(0)
	s_waitcnt vmcnt(0)
	v_mbcnt_lo_u32_b32 v1, s16, 0
	v_mbcnt_hi_u32_b32 v1, s17, v1
	v_cmp_eq_u32_e32 vcc, 0, v1
	s_and_saveexec_b64 s[28:29], vcc
	s_cbranch_execz .LBB0_1107
	s_bcnt1_i32_b64 s3, s[16:17]
	v_mov_b32_e32 v2, 0xed25000
	v_mov_b32_e32 v3, s3
	global_atomic_add v2, v2, v3, s[24:25] offset:1024 sc0

.LBB0_1220:
	s_or_b64 exec, exec, s[16:17]
	v_cvt_f32_u32_e32 v4, v2
	s_waitcnt vmcnt(0)
	v_readfirstlane_b32 s3, v3
	v_sub_u32_e32 v3, 0, v2
	v_rcp_iflag_f32_e32 v4, v4
	v_add_u32_e32 v5, s3, v1
	v_mul_f32_e32 v4, 0x4f7ffffe, v4
	v_cvt_u32_f32_e32 v4, v4
	v_mul_lo_u32 v1, v3, v4
	v_mul_hi_u32 v1, v4, v1
	v_add_u32_e32 v1, v4, v1
	v_mul_hi_u32 v1, v5, v1
	v_mul_lo_u32 v3, v1, v2
	v_sub_u32_e32 v3, v5, v3
	v_add_u32_e32 v4, 1, v1
	v_cmp_ge_u32_e32 vcc, v3, v2
	s_nop 1
	v_cndmask_b32_e32 v1, v1, v4, vcc
	v_sub_u32_e32 v4, v3, v2
	v_cndmask_b32_e32 v3, v3, v4, vcc
	v_add_u32_e32 v4, 1, v1
	v_cmp_ge_u32_e32 vcc, v3, v2
	v_add_u32_e32 v3, 1, v5
	s_nop 0
	v_cndmask_b32_e32 v1, v1, v4, vcc
	v_mul_lo_u32 v4, v2, v1
	v_add_u32_e32 v2, v4, v2
	v_cmp_ne_u32_e32 vcc, v3, v2
	s_and_saveexec_b64 s[6:7], vcc
	s_xor_b64 s[6:7], exec, s[6:7]
	s_cbranch_execz .LBB0_1234
	s_waitcnt lgkmcnt(0)
	buffer_inv sc1
	v_add_u32_e32 v1, 1, v1
	v_mul_lo_u32 v1, v1, v0
	s_add_u32 s40, s24, 0xed25400
	s_addc_u32 s41, s25, 0
	v_mov_b32_e32 v0, 0
	global_load_dword v0, v0, s[40:41] sc1
	s_waitcnt vmcnt(0)
	v_cmp_lt_u32_e32 vcc, v0, v1
	s_and_saveexec_b64 s[36:37], vcc
	s_cbranch_execz .LBB0_1233
	s_add_u32 s38, s24, 0xed22200
	s_addc_u32 s39, s25, 0
	s_mov_b32 s3, 1
	s_mov_b64 s[42:43], 0
	v_mov_b32_e32 v0, 0
	s_branch .LBB0_1224

.LBB0_1234:
	s_andn2_saveexec_b64 s[6:7], s[6:7]
	s_cbranch_execz .LBB0_1254
	s_mov_b64 s[6:7], exec
	buffer_wbl2 sc1
	buffer_inv sc1
	s_waitcnt lgkmcnt(0)
	s_waitcnt vmcnt(0)
	v_mbcnt_lo_u32_b32 v1, s6, 0
	v_mbcnt_hi_u32_b32 v1, s7, v1
	v_cmp_eq_u32_e32 vcc, 0, v1
	s_and_saveexec_b64 s[16:17], vcc
	s_cbranch_execz .LBB0_1237
	s_bcnt1_i32_b64 s3, s[6:7]
	v_mov_b32_e32 v2, 0xed25000
	v_mov_b32_e32 v3, s3
	global_atomic_add v2, v2, v3, s[24:25] offset:1024 sc0

.LBB0_1318:
	s_or_b64 exec, exec, s[14:15]
	v_cvt_f32_u32_e32 v4, v2
	s_waitcnt vmcnt(0)
	v_readfirstlane_b32 s3, v3
	v_sub_u32_e32 v3, 0, v2
	v_rcp_iflag_f32_e32 v4, v4
	v_add_u32_e32 v5, s3, v1
	v_mul_f32_e32 v4, 0x4f7ffffe, v4
	v_cvt_u32_f32_e32 v4, v4
	v_mul_lo_u32 v1, v3, v4
	v_mul_hi_u32 v1, v4, v1
	v_add_u32_e32 v1, v4, v1
	v_mul_hi_u32 v1, v5, v1
	v_mul_lo_u32 v3, v1, v2
	v_sub_u32_e32 v3, v5, v3
	v_add_u32_e32 v4, 1, v1
	v_cmp_ge_u32_e32 vcc, v3, v2
	s_nop 1
	v_cndmask_b32_e32 v1, v1, v4, vcc
	v_sub_u32_e32 v4, v3, v2
	v_cndmask_b32_e32 v3, v3, v4, vcc
	v_add_u32_e32 v4, 1, v1
	v_cmp_ge_u32_e32 vcc, v3, v2
	v_add_u32_e32 v3, 1, v5
	s_nop 0
	v_cndmask_b32_e32 v1, v1, v4, vcc
	v_mul_lo_u32 v4, v2, v1
	v_add_u32_e32 v2, v4, v2
	v_cmp_ne_u32_e32 vcc, v3, v2
	s_and_saveexec_b64 s[6:7], vcc
	s_xor_b64 s[6:7], exec, s[6:7]
	s_cbranch_execz .LBB0_1332
	s_waitcnt lgkmcnt(0)
	buffer_inv sc1
	v_add_u32_e32 v1, 1, v1
	v_mul_lo_u32 v1, v1, v0
	s_add_u32 s38, s24, 0xed25400
	s_addc_u32 s39, s25, 0
	v_mov_b32_e32 v0, 0
	global_load_dword v0, v0, s[38:39] sc1
	s_waitcnt vmcnt(0)
	v_cmp_lt_u32_e32 vcc, v0, v1
	s_and_saveexec_b64 s[14:15], vcc
	s_cbranch_execz .LBB0_1331
	s_add_u32 s36, s24, 0xed22200
	s_addc_u32 s37, s25, 0
	s_mov_b32 s3, 1
	s_mov_b64 s[40:41], 0
	v_mov_b32_e32 v0, 0
	s_branch .LBB0_1322

.LBB0_1332:
	s_andn2_saveexec_b64 s[6:7], s[6:7]
	s_cbranch_execz .LBB0_1352
	s_mov_b64 s[14:15], exec
	buffer_wbl2 sc1
	buffer_inv sc1
	s_waitcnt lgkmcnt(0)
	s_waitcnt vmcnt(0)
	v_mbcnt_lo_u32_b32 v1, s14, 0
	v_mbcnt_hi_u32_b32 v1, s15, v1
	v_cmp_eq_u32_e32 vcc, 0, v1
	s_and_saveexec_b64 s[16:17], vcc
	s_cbranch_execz .LBB0_1335
	s_bcnt1_i32_b64 s3, s[14:15]
	v_mov_b32_e32 v2, 0xed25000
	v_mov_b32_e32 v3, s3
	global_atomic_add v2, v2, v3, s[24:25] offset:1024 sc0

.LBB0_1522:
	s_or_b64 exec, exec, s[8:9]
	v_cvt_f32_u32_e32 v4, v2
	s_waitcnt vmcnt(0)
	v_readfirstlane_b32 s6, v3
	v_sub_u32_e32 v3, 0, v2
	v_rcp_iflag_f32_e32 v4, v4
	v_add_u32_e32 v5, s6, v1
	v_mul_f32_e32 v4, 0x4f7ffffe, v4
	v_cvt_u32_f32_e32 v4, v4
	v_mul_lo_u32 v1, v3, v4
	v_mul_hi_u32 v1, v4, v1
	v_add_u32_e32 v1, v4, v1
	v_mul_hi_u32 v1, v5, v1
	v_mul_lo_u32 v3, v1, v2
	v_sub_u32_e32 v3, v5, v3
	v_add_u32_e32 v4, 1, v1
	v_cmp_ge_u32_e32 vcc, v3, v2
	s_nop 1
	v_cndmask_b32_e32 v1, v1, v4, vcc
	v_sub_u32_e32 v4, v3, v2
	v_cndmask_b32_e32 v3, v3, v4, vcc
	v_add_u32_e32 v4, 1, v1
	v_cmp_ge_u32_e32 vcc, v3, v2
	v_add_u32_e32 v3, 1, v5
	s_nop 0
	v_cndmask_b32_e32 v1, v1, v4, vcc
	v_mul_lo_u32 v4, v2, v1
	v_add_u32_e32 v2, v4, v2
	v_cmp_ne_u32_e32 vcc, v3, v2
	s_and_saveexec_b64 s[6:7], vcc
	s_xor_b64 s[6:7], exec, s[6:7]
	s_cbranch_execz .LBB0_1536
	s_waitcnt lgkmcnt(0)
	buffer_inv sc1
	v_add_u32_e32 v1, 1, v1
	v_mul_lo_u32 v1, v1, v0
	s_add_u32 s14, s24, 0xed25400
	s_addc_u32 s15, s25, 0
	v_mov_b32_e32 v0, 0
	global_load_dword v0, v0, s[14:15] sc1
	s_waitcnt vmcnt(0)
	v_cmp_lt_u32_e32 vcc, v0, v1
	s_and_saveexec_b64 s[8:9], vcc
	s_cbranch_execz .LBB0_1535
	s_add_u32 s12, s24, 0xed22200
	s_addc_u32 s13, s25, 0
	s_mov_b32 s19, 1
	s_mov_b64 s[16:17], 0
	v_mov_b32_e32 v0, 0
	s_branch .LBB0_1526

.LBB0_1536:
	s_andn2_saveexec_b64 s[6:7], s[6:7]
	s_cbranch_execz .LBB0_1556
	s_mov_b64 s[6:7], exec
	buffer_wbl2 sc1
	buffer_inv sc1
	s_waitcnt lgkmcnt(0)
	s_waitcnt vmcnt(0)
	v_mbcnt_lo_u32_b32 v1, s6, 0
	v_mbcnt_hi_u32_b32 v1, s7, v1
	v_cmp_eq_u32_e32 vcc, 0, v1
	s_and_saveexec_b64 s[8:9], vcc
	s_cbranch_execz .LBB0_1539
	s_bcnt1_i32_b64 s6, s[6:7]
	v_mov_b32_e32 v2, 0xed25000
	v_mov_b32_e32 v3, s6
	global_atomic_add v2, v2, v3, s[24:25] offset:1024 sc0
